# ffn1 epilogue: the conv-weight / scale loads of the first column half issued before the halo-exchange barrier instead of after it
# speedup vs baseline: 1.0194x; 1.0004x over previous
;     __device__ __forceinline__ void operator()(const f32x4 (&acc)[2][2][4][2], const Unit& u, int wr_, int wc_, int fr_, int fq_) const {
;     ...
;         PG8_XBAR();
;         const bool is15 = fr == 15, ge14 = fr >= 14;
;         float GK1 = -2.885390081777927f * 0.7978845608028654f, GK2 = GK1 * 0.044715f; asm volatile("" : "+v"(GK1), "+v"(GK2));
;         u32x2 keep[2][4];
; #pragma unroll
;         for (int n = 0; n < 2; ++n) {
;             const int cn = c0 + 4 * n;
;             const f32x4 sa = *(const f32x4*)(sb8 + u.pn * 256 + cl0 + 4 * n), sg = *(const f32x4*)(sb8 + u.pn * 256 + 128 + cl0 + 4 * n);
;             const f32x4 w0 = *(const f32x4*)(cw + cn) * sa, w1 = *(const f32x4*)(cw + DFF + cn) * sa, w2 = *(const f32x4*)(cw + 2 * DFF + cn) * sa, cbv = *(const f32x4*)(cb + cn);
; #pragma unroll
;             for (int ai = 0; ai < 2; ++ai)
; #pragma unroll
;                 for (int m = 0; m < 4; ++m) {
;                     const int rt = ai * HALF + wr * 64 + m * 16 + fr, row = u.pm * BM + rt;
;                     const f32x4 ca = cvti4(acc[ai][0][m][n]) * rr[ai][m], ga = cvti4(acc[ai][1][m][n]) * rr[ai][m];
;                     f32x4 pa = {0.f, 0.f, 0.f, 0.f};
;                     if (m > 0) pa = cvti4(acc[ai][0][m - 1][n]) * rr[ai][m - 1];
;                     else if (fr >= 14) {
;                         const int which = wr == 1 ? ai * 2 : (ai == 1 ? 1 : -1);
;                         if (which >= 0) pa = *(const PG8_LAS f32x4*)(X + (which * 2 + (fr - 14)) * 128 + cl0 + 4 * n);
;                     }
;                     const f32x4 z1 = is15 ? pa : ca, z2 = ge14 ? pa : ca;
;                     f32x4 a1, a2, ex, rc;
; #pragma unroll
;                     for (int j = 0; j < 4; ++j) { a1[j] = rorf<0x121>(z1[j]); a2[j] = rorf<0x122>(z2[j]); }
;                     const f32x4 cv = cbv + w2 * ca + w1 * a1 + w0 * a2;
;                     const f32x4 ev = (cv * cv * GK2 + GK1) * cv;
; #pragma unroll
;                     for (int j = 0; j < 4; ++j) ex[j] = __builtin_amdgcn_exp2f(ev[j]);
;                     ex = ex + 1.f;
; #pragma unroll
;                     for (int j = 0; j < 4; ++j) rc[j] = __builtin_amdgcn_rcpf(ex[j]);
;                     const f32x4 oa = (cv * rc) * (ga * sg);
;                     u32x2 w; w.x = cvt_pk_bf16(oa[0], oa[1]); w.y = cvt_pk_bf16(oa[2], oa[3]);
;                     if (n == 0) keep[ai][m] = w;
.LBB0_2153:
	s_andn2_saveexec_b64 s[0:1], s[8:9]
	s_ashr_i32 s5, s4, 31
	s_lshl_b64 s[4:5], s[4:5], 1
	v_mov_b64_e32 v[32:33], s[4:5]
	s_or_b64 exec, exec, s[0:1]
	s_lshl_b32 s0, s86, 8
	s_ashr_i32 s1, s0, 31
	s_cmp_lg_u32 s37, 1
	s_cselect_b64 s[56:57], -1, 0
	s_lshl_b64 s[0:1], s[0:1], 2
	s_add_u32 s0, s71, s0
	v_ashrrev_i32_e32 v9, 31, v8
	s_addc_u32 s1, s72, s1
	v_lshlrev_b64 v[4:5], 2, v[166:167]
	v_mov_b32_e32 v104, 0xc0135761
	v_mov_b32_e32 v108, 0xbdd2d3e7
	v_lshl_add_u64 v[40:41], v[8:9], 2, s[0:1]
	v_lshl_add_u64 v[0:1], s[12:13], 0, v[4:5]
	global_load_dwordx4 v[10:13], v[40:41], off
	global_load_dwordx4 v[6:9], v[40:41], off offset:512
	v_lshl_add_u64 v[2:3], s[30:31], 0, v[4:5]
	global_load_dwordx4 v[26:29], v[0:1], off
	global_load_dwordx4 v[22:25], v[2:3], off
	v_lshl_add_u64 v[0:1], s[34:35], 0, v[4:5]
	global_load_dwordx4 v[18:21], v[0:1], off
	v_lshl_add_u64 v[0:1], s[14:15], 0, v[4:5]
	global_load_dwordx4 v[0:3], v[0:1], off
	s_waitcnt lgkmcnt(0)
	s_barrier
	v_cndmask_b32_e64 v14, 0, -1, s[56:57]
	v_lshlrev_b32_e32 v87, 9, v136
	v_readfirstlane_b32 s0, v14
	s_lshl_b32 s39, s0, 10
	s_nor_b64 s[48:49], vcc, s[56:57]
	v_mov_b32_e32 v14, 0
	v_mov_b32_e32 v15, 0
	v_mov_b32_e32 v16, 0
	v_mov_b32_e32 v17, 0
	s_and_saveexec_b64 s[0:1], s[48:49]
	s_add_i32 s4, s39, 0
	s_add_i32 s4, s4, 0x20400
	v_add_u32_e32 v14, s4, v87
	v_add3_u32 v14, v14, v81, s83
	ds_read_b128 v[14:17], v14
	s_or_b64 exec, exec, s[0:1]
	v_lshl_add_u64 v[224:225], v[32:33], 0, v[136:137]
	s_waitcnt vmcnt(0)
	v_pk_mul_f32 v[32:33], v[12:13], v[28:29]
	v_pk_mul_f32 v[26:27], v[10:11], v[26:27]
	v_pk_mul_f32 v[42:43], v[12:13], v[24:25]
	v_pk_mul_f32 v[34:35], v[10:11], v[22:23]
	v_pk_mul_f32 v[44:45], v[12:13], v[20:21]
	v_pk_mul_f32 v[46:47], v[10:11], v[18:19]
	v_pk_mul_f32 v[12:13], v[184:185], v[220:221] op_sel_hi:[0,1]
	v_pk_mul_f32 v[10:11], v[184:185], v[218:219] op_sel_hi:[0,1]
	v_cmp_eq_u32_e64 s[4:5], 15, v136
	s_waitcnt lgkmcnt(0)
	v_cndmask_b32_e32 v22, v17, v13, vcc
	v_cndmask_b32_e32 v23, v16, v12, vcc
	v_cndmask_b32_e64 v19, v13, v17, s[4:5]
	v_cndmask_b32_e64 v20, v11, v15, s[4:5]
	v_cndmask_b32_e64 v21, v10, v14, s[4:5]
	v_cndmask_b32_e32 v17, v15, v11, vcc
	v_cndmask_b32_e32 v15, v14, v10, vcc
	v_cndmask_b32_e64 v18, v12, v16, s[4:5]
	v_mov_b32_dpp v14, v21 row_ror:1 row_mask:0xf bank_mask:0xf bound_ctrl:1
	v_mov_b32_dpp v16, v15 row_ror:2 row_mask:0xf bank_mask:0xf bound_ctrl:1
	v_mov_b32_dpp v15, v20 row_ror:1 row_mask:0xf bank_mask:0xf bound_ctrl:1
	v_pk_fma_f32 v[24:25], v[10:11], v[46:47], v[0:1]
	v_mov_b32_dpp v17, v17 row_ror:2 row_mask:0xf bank_mask:0xf bound_ctrl:1
	v_mov_b32_dpp v18, v18 row_ror:1 row_mask:0xf bank_mask:0xf bound_ctrl:1
	v_mov_b32_dpp v20, v23 row_ror:2 row_mask:0xf bank_mask:0xf bound_ctrl:1
	v_mov_b32_dpp v19, v19 row_ror:1 row_mask:0xf bank_mask:0xf bound_ctrl:1
	v_mov_b32_dpp v21, v22 row_ror:2 row_mask:0xf bank_mask:0xf bound_ctrl:1
	v_pk_fma_f32 v[22:23], v[12:13], v[44:45], v[2:3]
	v_pk_fma_f32 v[14:15], v[34:35], v[14:15], v[24:25]
	v_pk_fma_f32 v[18:19], v[42:43], v[18:19], v[22:23]
	v_pk_fma_f32 v[22:23], v[26:27], v[16:17], v[14:15]
	v_pk_fma_f32 v[18:19], v[32:33], v[20:21], v[18:19]
	v_pk_mul_f32 v[16:17], v[22:23], v[22:23]
	v_pk_mul_f32 v[14:15], v[18:19], v[18:19]
	v_pk_fma_f32 v[16:17], v[108:109], v[16:17], v[104:105] op_sel_hi:[0,1,0]
	v_pk_fma_f32 v[14:15], v[108:109], v[14:15], v[104:105] op_sel_hi:[0,1,0]
	v_pk_mul_f32 v[16:17], v[22:23], v[16:17]
	v_pk_mul_f32 v[14:15], v[18:19], v[14:15]
	v_exp_f32_e32 v16, v16
	v_exp_f32_e32 v17, v17
	v_exp_f32_e32 v14, v14
	v_exp_f32_e32 v15, v15
	v_mad_u64_u32 v[226:227], s[0:1], v224, s82, 0
	v_mov_b32_e32 v224, v227
	v_mad_u64_u32 v[20:21], s[0:1], v225, s82, v[224:225]
	v_pk_add_f32 v[16:17], v[16:17], 1.0 op_sel_hi:[1,0]
	v_mov_b32_e32 v227, v20
	v_pk_add_f32 v[14:15], v[14:15], 1.0 op_sel_hi:[1,0]
	v_rcp_f32_e32 v20, v16
	v_rcp_f32_e32 v21, v17
	v_rcp_f32_e32 v24, v14
	v_rcp_f32_e32 v25, v15
	v_pk_mul_f32 v[14:15], v[184:185], v[214:215] op_sel_hi:[0,1]
	s_cmp_eq_u32 s37, 0
	v_cmp_gt_u32_e64 s[8:9], 2, v136
	v_pk_mul_f32 v[16:17], v[184:185], v[216:217] op_sel_hi:[0,1]
	v_pk_mul_f32 v[20:21], v[22:23], v[20:21]
	v_pk_mul_f32 v[22:23], v[14:15], v[6:7]
	s_cselect_b64 s[0:1], -1, 0
	v_pk_mul_f32 v[18:19], v[18:19], v[24:25]
	v_pk_mul_f32 v[24:25], v[16:17], v[8:9]
	v_pk_mul_f32 v[20:21], v[22:23], v[20:21]
	s_and_b64 s[8:9], s[0:1], s[8:9]
	v_lshl_add_u64 v[214:215], s[20:21], 0, v[226:227]
	v_lshl_add_u64 v[216:217], s[22:23], 0, v[226:227]
	v_pk_mul_f32 v[18:19], v[24:25], v[18:19]
	v_cvt_pk_bf16_f32 v20, v20, v21
	s_nop 0
	v_cvt_pk_bf16_f32 v21, v18, v19
	s_and_saveexec_b64 s[0:1], s[8:9]
	s_cbranch_execz .LBB0_2159
	v_lshl_add_u64 v[18:19], v[214:215], 0, v[4:5]
	v_lshl_add_u64 v[4:5], v[216:217], 0, v[4:5]
	global_store_dwordx4 v[18:19], v[10:13], off
	global_store_dwordx4 v[4:5], v[14:17], off
